# PA column tiles 8 (gk/gv, heavy epilogue) and 10 (GLU) swap owner groups so the critical group gets a light tile; dk tile group no longer delayed
# speedup vs baseline: 1.0170x; 1.0028x over previous
.LBB0_388:
	s_cmp_eq_u32 s18, 8
	s_cbranch_scc1 .Lsw_a
	s_cmp_eq_u32 s18, 10
	s_cbranch_scc0 .Lsw_done
	s_mov_b32 s18, 8
	s_branch .Lsw_done
.Lsw_a:
	s_mov_b32 s18, 10

.LBB0_392:
	s_cmp_lt_u32 s72, 3
	s_cbranch_scc1 .Lpd_skip
	s_cmp_gt_u32 s72, 5
	s_cbranch_scc1 .Lpd_skip
	s_sleep 127
	s_sleep 127
	s_sleep 127

.Lg4_loop:
	s_mul_i32 s70, s84, 0x9000
	v_add_u32_e32 v208, s70, v154
	s_mov_b32 s71, s65
	s_mul_i32 s68, s71, 0x9000
	s_mov_b32 s65, s84
	v_add_u32_e32 v209, s68, v155
	v_add_u32_e32 v210, 0x4000, v209
	v_add_u32_e32 v211, 0x5000, v209
	ds_read_b128 v[156:159], v208
	ds_read_b128 v[160:163], v208 offset:4608
	ds_read_b128 v[164:167], v208 offset:32
	ds_read_b128 v[168:171], v208 offset:4640
	ds_read_b128 v[172:175], v208 offset:64
	ds_read_b128 v[176:179], v208 offset:4672
	ds_read_b128 v[184:187], v208 offset:96
	ds_read_b128 v[188:191], v208 offset:4704
	s_mul_i32 s72, s66, 0x9000
	s_add_i32 s73, s72, 0
	v_add3_u32 v218, s73, v150, v151
	v_add3_u32 v219, s73, v152, v153
	v_exp_f32_e32 v64, v64
	v_exp_f32_e32 v80, v80
	v_exp_f32_e32 v65, v65
	v_exp_f32_e32 v81, v81
	v_exp_f32_e32 v66, v66
	s_waitcnt lgkmcnt(6)
	v_mfma_f32_32x32x16_bf16 v[48:63], v[156:159], v[108:111], v[32:47]
	ds_read2_b64 v[156:159], v210 offset0:128 offset1:130
	v_pk_add_f32 v[214:215], v[64:65], v[80:81]
	v_exp_f32_e32 v82, v82
	v_exp_f32_e32 v67, v67
	v_exp_f32_e32 v83, v83
	v_mfma_f32_32x32x16_bf16 v[192:207], v[160:163], v[108:111], v[32:47]
	ds_read2_b64 v[160:163], v211 offset0:192 offset1:194
	s_waitcnt vmcnt(0)
	ds_write_b128 v218, v[116:119]
	ds_write_b128 v219, v[124:127] offset:17408
	s_add_i32 s68, s25, -2
	s_cmp_gt_u32 s68, 33
	s_cbranch_scc1 .Lg4b_nogl
	s_cmp_lt_u32 s68, 30
	s_cselect_b64 s[74:75], -1, 0
	s_and_b64 s[76:77], s[74:75], exec
	s_cselect_b32 s68, 0, 0xffffffe0
	s_add_i32 s68, s68, s25
	s_and_b64 s[76:77], s[74:75], exec
	s_cselect_b32 s73, s21, s27
	s_cselect_b32 s78, s20, s26
	s_lshl_b64 s[76:77], s[68:69], 14
	s_add_u32 s76, s78, s76
	s_addc_u32 s77, s73, s77
	s_and_b64 s[78:79], s[74:75], exec
	s_cselect_b32 s73, s23, s64
	s_cselect_b32 s80, s22, s63
	s_lshl_b32 s68, s68, 6
	s_lshl_b64 s[78:79], s[68:69], 1
	s_add_u32 s78, s80, s78
	s_addc_u32 s79, s73, s79
	v_lshl_add_u64 v[222:223], v[142:143], 1, s[76:77]
	s_and_b64 s[74:75], s[74:75], exec
	v_lshl_add_u64 v[222:223], v[144:145], 1, v[222:223]
	s_cselect_b32 s68, 11, 8
	global_load_dwordx4 v[116:119], v[222:223], off
	v_lshlrev_b64 v[222:223], s68, v[146:147]
	v_lshl_add_u64 v[222:223], v[222:223], 1, s[78:79]
	v_lshl_add_u64 v[222:223], v[222:223], 0, v[128:129]
	global_load_dwordx4 v[124:127], v[222:223], off
.Lg4b_nogl:
	s_waitcnt lgkmcnt(8)
	v_mfma_f32_32x32x16_bf16 v[48:63], v[164:167], v[104:107], v[48:63]
	ds_read2_b64 v[164:167], v210 offset0:136 offset1:138
	v_exp_f32_e32 v68, v68
	v_pk_add_f32 v[212:213], v[66:67], v[82:83]
	v_pk_add_f32 v[214:215], v[214:215], v[212:213]
	v_exp_f32_e32 v84, v84
	v_mfma_f32_32x32x16_bf16 v[192:207], v[168:171], v[104:107], v[192:207]
	ds_read2_b64 v[168:171], v211 offset0:200 offset1:202
	v_exp_f32_e32 v69, v69
	v_exp_f32_e32 v85, v85
	v_exp_f32_e32 v70, v70
	v_pk_add_f32 v[212:213], v[68:69], v[84:85]
	s_waitcnt lgkmcnt(8)
	v_mfma_f32_32x32x16_bf16 v[48:63], v[172:175], v[100:103], v[48:63]
	ds_read2_b64 v[172:175], v210 offset0:132 offset1:134
	v_pk_add_f32 v[214:215], v[214:215], v[212:213]
	v_exp_f32_e32 v86, v86
	v_exp_f32_e32 v71, v71
	v_exp_f32_e32 v87, v87
	v_mfma_f32_32x32x16_bf16 v[192:207], v[176:179], v[100:103], v[192:207]
	ds_read2_b64 v[176:179], v211 offset0:196 offset1:198
	v_cvt_pk_bf16_f32 v134, v64, v65
	v_pk_add_f32 v[212:213], v[70:71], v[86:87]
	v_pk_add_f32 v[214:215], v[214:215], v[212:213]
	v_cvt_pk_bf16_f32 v135, v66, v67
	v_cvt_pk_bf16_f32 v136, v68, v69
	v_cvt_pk_bf16_f32 v137, v70, v71
	s_waitcnt lgkmcnt(8)
	v_mfma_f32_32x32x16_bf16 v[48:63], v[184:187], v[96:99], v[48:63]
	ds_read2_b64 v[184:187], v210 offset0:140 offset1:142
	v_cvt_pk_bf16_f32 v120, v80, v81
	v_cvt_pk_bf16_f32 v121, v82, v83
	v_cvt_pk_bf16_f32 v122, v84, v85
	v_cvt_pk_bf16_f32 v123, v86, v87
	v_mfma_f32_32x32x16_bf16 v[192:207], v[188:191], v[96:99], v[192:207]
	ds_read2_b64 v[188:191], v211 offset0:204 offset1:206
	s_waitcnt lgkmcnt(8)
	v_mfma_f32_32x32x16_bf16 v[16:31], v[156:159], v[134:137], v[16:31]
	v_exp_f32_e32 v72, v72
	v_exp_f32_e32 v88, v88
	v_exp_f32_e32 v73, v73
	v_exp_f32_e32 v89, v89
	v_exp_f32_e32 v74, v74
	v_pk_add_f32 v[212:213], v[72:73], v[88:89]
	v_mfma_f32_32x32x16_bf16 v[0:15], v[160:163], v[134:137], v[0:15]
	v_pk_add_f32 v[214:215], v[214:215], v[212:213]
	v_exp_f32_e32 v90, v90
	v_exp_f32_e32 v75, v75
	v_exp_f32_e32 v91, v91
	v_exp_f32_e32 v76, v76
	v_pk_add_f32 v[212:213], v[74:75], v[90:91]
	s_waitcnt lgkmcnt(4)
	v_mfma_f32_32x32x16_bf16 v[16:31], v[164:167], v[120:123], v[16:31]
	v_pk_add_f32 v[214:215], v[214:215], v[212:213]
	v_exp_f32_e32 v92, v92
	v_exp_f32_e32 v77, v77
	v_exp_f32_e32 v93, v93
	v_exp_f32_e32 v78, v78
	v_mfma_f32_32x32x16_bf16 v[0:15], v[168:171], v[120:123], v[0:15]
	v_pk_add_f32 v[212:213], v[76:77], v[92:93]
	v_pk_add_f32 v[214:215], v[214:215], v[212:213]
	v_exp_f32_e32 v94, v94
	v_exp_f32_e32 v79, v79
	v_exp_f32_e32 v95, v95
	v_cvt_pk_bf16_f32 v130, v72, v73
	v_pk_add_f32 v[212:213], v[78:79], v[94:95]
	v_pk_add_f32 v[214:215], v[214:215], v[212:213]
	v_cvt_pk_bf16_f32 v131, v74, v75
	v_cvt_pk_bf16_f32 v132, v76, v77
	v_cvt_pk_bf16_f32 v133, v78, v79
	s_waitcnt lgkmcnt(2)
	s_nop 0
	v_mfma_f32_32x32x16_bf16 v[16:31], v[172:175], v[130:133], v[16:31]
	v_cvt_pk_bf16_f32 v112, v88, v89
	v_cvt_pk_bf16_f32 v113, v90, v91
	v_cvt_pk_bf16_f32 v114, v92, v93
	v_cvt_pk_bf16_f32 v115, v94, v95
	v_add_f32_e32 v212, v214, v215
	v_add_f32_e32 v148, v148, v212
	v_mfma_f32_32x32x16_bf16 v[0:15], v[176:179], v[130:133], v[0:15]
	v_max3_f32 v212, v48, v192, v52
	v_max3_f32 v213, v49, v193, v53
	v_max3_f32 v214, v50, v194, v54
	v_max3_f32 v215, v51, v195, v55
	v_max3_f32 v212, v212, v196, v56
	v_max3_f32 v213, v213, v197, v57
	v_max3_f32 v214, v214, v198, v58
	v_max3_f32 v215, v215, v199, v59
	v_max3_f32 v212, v212, v200, v60
	s_waitcnt lgkmcnt(0)
	v_mfma_f32_32x32x16_bf16 v[16:31], v[184:187], v[112:115], v[16:31]
	v_max3_f32 v213, v213, v201, v61
	v_max3_f32 v214, v214, v202, v62
	v_max3_f32 v215, v215, v203, v63
	v_max_f32_e32 v212, v212, v204
	v_max_f32_e32 v213, v213, v205
	v_max_f32_e32 v214, v214, v206
	v_max_f32_e32 v215, v215, v207
	v_max3_f32 v212, v212, v213, v214
	v_max_f32_e32 v212, v212, v215
	v_mfma_f32_32x32x16_bf16 v[0:15], v[188:191], v[112:115], v[0:15]
	v_mov_b32_e32 v216, v212
	v_mov_b32_e32 v217, v212
	s_nop 1
	v_permlane32_swap_b32_e32 v216, v217
	v_max_f32_e32 v212, v216, v217
	v_cmp_lt_f32_e32 vcc, 0x41000000, v212
	s_cbranch_vccz .Lg4b_join
	v_max_f32_e32 v222, 0, v212
	v_add_f32_e32 v149, v149, v222
	v_exp_f32_e64 v216, -v222
	v_xor_b32_e32 v32, 0x80000000, v149
	v_pk_add_f32 v[48:49], v[48:49], v[222:223] op_sel_hi:[1,0] neg_lo:[0,1] neg_hi:[0,1]
	v_pk_add_f32 v[50:51], v[50:51], v[222:223] op_sel_hi:[1,0] neg_lo:[0,1] neg_hi:[0,1]
	v_pk_add_f32 v[52:53], v[52:53], v[222:223] op_sel_hi:[1,0] neg_lo:[0,1] neg_hi:[0,1]
	v_pk_add_f32 v[54:55], v[54:55], v[222:223] op_sel_hi:[1,0] neg_lo:[0,1] neg_hi:[0,1]
	v_pk_add_f32 v[56:57], v[56:57], v[222:223] op_sel_hi:[1,0] neg_lo:[0,1] neg_hi:[0,1]
	v_pk_add_f32 v[58:59], v[58:59], v[222:223] op_sel_hi:[1,0] neg_lo:[0,1] neg_hi:[0,1]
	v_pk_add_f32 v[60:61], v[60:61], v[222:223] op_sel_hi:[1,0] neg_lo:[0,1] neg_hi:[0,1]
	v_pk_add_f32 v[62:63], v[62:63], v[222:223] op_sel_hi:[1,0] neg_lo:[0,1] neg_hi:[0,1]
	v_pk_add_f32 v[192:193], v[192:193], v[222:223] op_sel_hi:[1,0] neg_lo:[0,1] neg_hi:[0,1]
	v_pk_add_f32 v[194:195], v[194:195], v[222:223] op_sel_hi:[1,0] neg_lo:[0,1] neg_hi:[0,1]
	v_pk_add_f32 v[196:197], v[196:197], v[222:223] op_sel_hi:[1,0] neg_lo:[0,1] neg_hi:[0,1]
	v_pk_add_f32 v[198:199], v[198:199], v[222:223] op_sel_hi:[1,0] neg_lo:[0,1] neg_hi:[0,1]
	v_pk_add_f32 v[200:201], v[200:201], v[222:223] op_sel_hi:[1,0] neg_lo:[0,1] neg_hi:[0,1]
	v_pk_add_f32 v[202:203], v[202:203], v[222:223] op_sel_hi:[1,0] neg_lo:[0,1] neg_hi:[0,1]
	v_pk_add_f32 v[204:205], v[204:205], v[222:223] op_sel_hi:[1,0] neg_lo:[0,1] neg_hi:[0,1]
	v_pk_add_f32 v[206:207], v[206:207], v[222:223] op_sel_hi:[1,0] neg_lo:[0,1] neg_hi:[0,1]
	v_mov_b32_e32 v33, v32
	v_mov_b32_e32 v34, v32
	v_mov_b32_e32 v35, v32
	v_mov_b32_e32 v36, v32
	v_mov_b32_e32 v37, v32
	v_mov_b32_e32 v38, v32
	v_mov_b32_e32 v39, v32
	v_mov_b32_e32 v40, v32
	v_mov_b32_e32 v41, v32
	v_mov_b32_e32 v42, v32
	v_mov_b32_e32 v43, v32
	v_mov_b32_e32 v44, v32
	v_mov_b32_e32 v45, v32
	v_mov_b32_e32 v46, v32
	v_mov_b32_e32 v47, v32
	v_mul_f32_e32 v148, v148, v216
	v_pk_mul_f32 v[16:17], v[16:17], v[216:217] op_sel_hi:[1,0]
	v_pk_mul_f32 v[18:19], v[18:19], v[216:217] op_sel_hi:[1,0]
	v_pk_mul_f32 v[20:21], v[20:21], v[216:217] op_sel_hi:[1,0]
	v_pk_mul_f32 v[22:23], v[22:23], v[216:217] op_sel_hi:[1,0]
	v_pk_mul_f32 v[24:25], v[24:25], v[216:217] op_sel_hi:[1,0]
	v_pk_mul_f32 v[26:27], v[26:27], v[216:217] op_sel_hi:[1,0]
	v_pk_mul_f32 v[28:29], v[28:29], v[216:217] op_sel_hi:[1,0]
	v_pk_mul_f32 v[30:31], v[30:31], v[216:217] op_sel_hi:[1,0]
	v_pk_mul_f32 v[0:1], v[0:1], v[216:217] op_sel_hi:[1,0]
	v_pk_mul_f32 v[2:3], v[2:3], v[216:217] op_sel_hi:[1,0]
	v_pk_mul_f32 v[4:5], v[4:5], v[216:217] op_sel_hi:[1,0]
	v_pk_mul_f32 v[6:7], v[6:7], v[216:217] op_sel_hi:[1,0]
	v_pk_mul_f32 v[8:9], v[8:9], v[216:217] op_sel_hi:[1,0]
	v_pk_mul_f32 v[10:11], v[10:11], v[216:217] op_sel_hi:[1,0]
	v_pk_mul_f32 v[12:13], v[12:13], v[216:217] op_sel_hi:[1,0]
	v_pk_mul_f32 v[14:15], v[14:15], v[216:217] op_sel_hi:[1,0]
.Lg4b_join:
	s_add_i32 s25, s25, 1
	s_cmp_lg_u32 s25, 37
	s_barrier
	s_cbranch_scc0 .Lg4_exit
	s_mov_b32 s84, s66
	s_mov_b32 s66, s71
	s_mul_i32 s70, s84, 0x9000
	v_add_u32_e32 v208, s70, v154
	s_mov_b32 s71, s65
	s_mul_i32 s68, s71, 0x9000
	s_mov_b32 s65, s84
	v_add_u32_e32 v209, s68, v155
	v_add_u32_e32 v210, 0x4000, v209
	v_add_u32_e32 v211, 0x5000, v209
	ds_read_b128 v[156:159], v208
	ds_read_b128 v[160:163], v208 offset:4608
	ds_read_b128 v[164:167], v208 offset:32
	ds_read_b128 v[168:171], v208 offset:4640
	ds_read_b128 v[172:175], v208 offset:64
	ds_read_b128 v[176:179], v208 offset:4672
	ds_read_b128 v[184:187], v208 offset:96
	ds_read_b128 v[188:191], v208 offset:4704
	s_mul_i32 s72, s66, 0x9000
	s_add_i32 s73, s72, 0
	v_add3_u32 v218, s73, v150, v151
	v_add3_u32 v219, s73, v152, v153
	v_exp_f32_e32 v48, v48
	v_exp_f32_e32 v192, v192
	v_exp_f32_e32 v49, v49
	v_exp_f32_e32 v193, v193
	v_exp_f32_e32 v50, v50
	s_waitcnt lgkmcnt(6)
	v_mfma_f32_32x32x16_bf16 v[64:79], v[156:159], v[108:111], v[32:47]
	ds_read2_b64 v[156:159], v210 offset0:128 offset1:130
	v_pk_add_f32 v[214:215], v[48:49], v[192:193]
	v_exp_f32_e32 v194, v194
	v_exp_f32_e32 v51, v51
	v_exp_f32_e32 v195, v195
	v_mfma_f32_32x32x16_bf16 v[80:95], v[160:163], v[108:111], v[32:47]
	ds_read2_b64 v[160:163], v211 offset0:192 offset1:194
	s_waitcnt vmcnt(0)
	ds_write_b128 v218, v[116:119]
	ds_write_b128 v219, v[124:127] offset:17408
	s_add_i32 s68, s25, -2
	s_cmp_gt_u32 s68, 33
	s_cbranch_scc1 .Lg4a_nogl
	s_cmp_lt_u32 s68, 30
	s_cselect_b64 s[74:75], -1, 0
	s_and_b64 s[76:77], s[74:75], exec
	s_cselect_b32 s68, 0, 0xffffffe0
	s_add_i32 s68, s68, s25
	s_and_b64 s[76:77], s[74:75], exec
	s_cselect_b32 s73, s21, s27
	s_cselect_b32 s78, s20, s26
	s_lshl_b64 s[76:77], s[68:69], 14
	s_add_u32 s76, s78, s76
	s_addc_u32 s77, s73, s77
	s_and_b64 s[78:79], s[74:75], exec
	s_cselect_b32 s73, s23, s64
	s_cselect_b32 s80, s22, s63
	s_lshl_b32 s68, s68, 6
	s_lshl_b64 s[78:79], s[68:69], 1
	s_add_u32 s78, s80, s78
	s_addc_u32 s79, s73, s79
	v_lshl_add_u64 v[222:223], v[142:143], 1, s[76:77]
	s_and_b64 s[74:75], s[74:75], exec
	v_lshl_add_u64 v[222:223], v[144:145], 1, v[222:223]
	s_cselect_b32 s68, 11, 8
	global_load_dwordx4 v[116:119], v[222:223], off
	v_lshlrev_b64 v[222:223], s68, v[146:147]
	v_lshl_add_u64 v[222:223], v[222:223], 1, s[78:79]
	v_lshl_add_u64 v[222:223], v[222:223], 0, v[128:129]
	global_load_dwordx4 v[124:127], v[222:223], off
.Lg4a_nogl:
	s_waitcnt lgkmcnt(8)
	v_mfma_f32_32x32x16_bf16 v[64:79], v[164:167], v[104:107], v[64:79]
	ds_read2_b64 v[164:167], v210 offset0:136 offset1:138
	v_exp_f32_e32 v52, v52
	v_pk_add_f32 v[212:213], v[50:51], v[194:195]
	v_pk_add_f32 v[214:215], v[214:215], v[212:213]
	v_exp_f32_e32 v196, v196
	v_mfma_f32_32x32x16_bf16 v[80:95], v[168:171], v[104:107], v[80:95]
	ds_read2_b64 v[168:171], v211 offset0:200 offset1:202
	v_exp_f32_e32 v53, v53
	v_exp_f32_e32 v197, v197
	v_exp_f32_e32 v54, v54
	v_pk_add_f32 v[212:213], v[52:53], v[196:197]
	s_waitcnt lgkmcnt(8)
	v_mfma_f32_32x32x16_bf16 v[64:79], v[172:175], v[100:103], v[64:79]
	ds_read2_b64 v[172:175], v210 offset0:132 offset1:134
	v_pk_add_f32 v[214:215], v[214:215], v[212:213]
	v_exp_f32_e32 v198, v198
	v_exp_f32_e32 v55, v55
	v_exp_f32_e32 v199, v199
	v_mfma_f32_32x32x16_bf16 v[80:95], v[176:179], v[100:103], v[80:95]
	ds_read2_b64 v[176:179], v211 offset0:196 offset1:198
	v_cvt_pk_bf16_f32 v134, v48, v49
	v_pk_add_f32 v[212:213], v[54:55], v[198:199]
	v_pk_add_f32 v[214:215], v[214:215], v[212:213]
	v_cvt_pk_bf16_f32 v135, v50, v51
	v_cvt_pk_bf16_f32 v136, v52, v53
	v_cvt_pk_bf16_f32 v137, v54, v55
	s_waitcnt lgkmcnt(8)
	v_mfma_f32_32x32x16_bf16 v[64:79], v[184:187], v[96:99], v[64:79]
	ds_read2_b64 v[184:187], v210 offset0:140 offset1:142
	v_cvt_pk_bf16_f32 v120, v192, v193
	v_cvt_pk_bf16_f32 v121, v194, v195
	v_cvt_pk_bf16_f32 v122, v196, v197
	v_cvt_pk_bf16_f32 v123, v198, v199
	v_mfma_f32_32x32x16_bf16 v[80:95], v[188:191], v[96:99], v[80:95]
	ds_read2_b64 v[188:191], v211 offset0:204 offset1:206
	s_waitcnt lgkmcnt(8)
	v_mfma_f32_32x32x16_bf16 v[16:31], v[156:159], v[134:137], v[16:31]
	v_exp_f32_e32 v56, v56
	v_exp_f32_e32 v200, v200
	v_exp_f32_e32 v57, v57
	v_exp_f32_e32 v201, v201
	v_exp_f32_e32 v58, v58
	v_pk_add_f32 v[212:213], v[56:57], v[200:201]
	v_mfma_f32_32x32x16_bf16 v[0:15], v[160:163], v[134:137], v[0:15]
	v_pk_add_f32 v[214:215], v[214:215], v[212:213]
	v_exp_f32_e32 v202, v202
	v_exp_f32_e32 v59, v59
	v_exp_f32_e32 v203, v203
	v_exp_f32_e32 v60, v60
	v_pk_add_f32 v[212:213], v[58:59], v[202:203]
	s_waitcnt lgkmcnt(4)
	v_mfma_f32_32x32x16_bf16 v[16:31], v[164:167], v[120:123], v[16:31]
	v_pk_add_f32 v[214:215], v[214:215], v[212:213]
	v_exp_f32_e32 v204, v204
	v_exp_f32_e32 v61, v61
	v_exp_f32_e32 v205, v205
	v_exp_f32_e32 v62, v62
	v_mfma_f32_32x32x16_bf16 v[0:15], v[168:171], v[120:123], v[0:15]
	v_pk_add_f32 v[212:213], v[60:61], v[204:205]
	v_pk_add_f32 v[214:215], v[214:215], v[212:213]
	v_exp_f32_e32 v206, v206
	v_exp_f32_e32 v63, v63
	v_exp_f32_e32 v207, v207
	v_cvt_pk_bf16_f32 v130, v56, v57
	v_pk_add_f32 v[212:213], v[62:63], v[206:207]
	v_pk_add_f32 v[214:215], v[214:215], v[212:213]
	v_cvt_pk_bf16_f32 v131, v58, v59
	v_cvt_pk_bf16_f32 v132, v60, v61
	v_cvt_pk_bf16_f32 v133, v62, v63
	s_waitcnt lgkmcnt(2)
	s_nop 0
	v_mfma_f32_32x32x16_bf16 v[16:31], v[172:175], v[130:133], v[16:31]
	v_cvt_pk_bf16_f32 v112, v200, v201
	v_cvt_pk_bf16_f32 v113, v202, v203
	v_cvt_pk_bf16_f32 v114, v204, v205
	v_cvt_pk_bf16_f32 v115, v206, v207
	v_add_f32_e32 v212, v214, v215
	v_add_f32_e32 v148, v148, v212
	v_mfma_f32_32x32x16_bf16 v[0:15], v[176:179], v[130:133], v[0:15]
	v_max3_f32 v212, v64, v80, v68
	v_max3_f32 v213, v65, v81, v69
	v_max3_f32 v214, v66, v82, v70
	v_max3_f32 v215, v67, v83, v71
	v_max3_f32 v212, v212, v84, v72
	v_max3_f32 v213, v213, v85, v73
	v_max3_f32 v214, v214, v86, v74
	v_max3_f32 v215, v215, v87, v75
	v_max3_f32 v212, v212, v88, v76
	s_waitcnt lgkmcnt(0)
	v_mfma_f32_32x32x16_bf16 v[16:31], v[184:187], v[112:115], v[16:31]
	v_max3_f32 v213, v213, v89, v77
	v_max3_f32 v214, v214, v90, v78
	v_max3_f32 v215, v215, v91, v79
	v_max_f32_e32 v212, v212, v92
	v_max_f32_e32 v213, v213, v93
	v_max_f32_e32 v214, v214, v94
	v_max_f32_e32 v215, v215, v95
	v_max3_f32 v212, v212, v213, v214
	v_max_f32_e32 v212, v212, v215
	v_mfma_f32_32x32x16_bf16 v[0:15], v[188:191], v[112:115], v[0:15]
	v_mov_b32_e32 v216, v212
	v_mov_b32_e32 v217, v212
	s_nop 1
	v_permlane32_swap_b32_e32 v216, v217
	v_max_f32_e32 v212, v216, v217
	v_cmp_lt_f32_e32 vcc, 0x41000000, v212
	s_cbranch_vccz .Lg4a_join
	v_max_f32_e32 v222, 0, v212
	v_add_f32_e32 v149, v149, v222
	v_exp_f32_e64 v216, -v222
	v_xor_b32_e32 v32, 0x80000000, v149
	v_pk_add_f32 v[64:65], v[64:65], v[222:223] op_sel_hi:[1,0] neg_lo:[0,1] neg_hi:[0,1]
	v_pk_add_f32 v[66:67], v[66:67], v[222:223] op_sel_hi:[1,0] neg_lo:[0,1] neg_hi:[0,1]
	v_pk_add_f32 v[68:69], v[68:69], v[222:223] op_sel_hi:[1,0] neg_lo:[0,1] neg_hi:[0,1]
	v_pk_add_f32 v[70:71], v[70:71], v[222:223] op_sel_hi:[1,0] neg_lo:[0,1] neg_hi:[0,1]
	v_pk_add_f32 v[72:73], v[72:73], v[222:223] op_sel_hi:[1,0] neg_lo:[0,1] neg_hi:[0,1]
	v_pk_add_f32 v[74:75], v[74:75], v[222:223] op_sel_hi:[1,0] neg_lo:[0,1] neg_hi:[0,1]
	v_pk_add_f32 v[76:77], v[76:77], v[222:223] op_sel_hi:[1,0] neg_lo:[0,1] neg_hi:[0,1]
	v_pk_add_f32 v[78:79], v[78:79], v[222:223] op_sel_hi:[1,0] neg_lo:[0,1] neg_hi:[0,1]
	v_pk_add_f32 v[80:81], v[80:81], v[222:223] op_sel_hi:[1,0] neg_lo:[0,1] neg_hi:[0,1]
	v_pk_add_f32 v[82:83], v[82:83], v[222:223] op_sel_hi:[1,0] neg_lo:[0,1] neg_hi:[0,1]
	v_pk_add_f32 v[84:85], v[84:85], v[222:223] op_sel_hi:[1,0] neg_lo:[0,1] neg_hi:[0,1]
	v_pk_add_f32 v[86:87], v[86:87], v[222:223] op_sel_hi:[1,0] neg_lo:[0,1] neg_hi:[0,1]
	v_pk_add_f32 v[88:89], v[88:89], v[222:223] op_sel_hi:[1,0] neg_lo:[0,1] neg_hi:[0,1]
	v_pk_add_f32 v[90:91], v[90:91], v[222:223] op_sel_hi:[1,0] neg_lo:[0,1] neg_hi:[0,1]
	v_pk_add_f32 v[92:93], v[92:93], v[222:223] op_sel_hi:[1,0] neg_lo:[0,1] neg_hi:[0,1]
	v_pk_add_f32 v[94:95], v[94:95], v[222:223] op_sel_hi:[1,0] neg_lo:[0,1] neg_hi:[0,1]
	v_mov_b32_e32 v33, v32
	v_mov_b32_e32 v34, v32
	v_mov_b32_e32 v35, v32
	v_mov_b32_e32 v36, v32
	v_mov_b32_e32 v37, v32
	v_mov_b32_e32 v38, v32
	v_mov_b32_e32 v39, v32
	v_mov_b32_e32 v40, v32
	v_mov_b32_e32 v41, v32
	v_mov_b32_e32 v42, v32
	v_mov_b32_e32 v43, v32
	v_mov_b32_e32 v44, v32
	v_mov_b32_e32 v45, v32
	v_mov_b32_e32 v46, v32
	v_mov_b32_e32 v47, v32
	v_mul_f32_e32 v148, v148, v216
	v_pk_mul_f32 v[16:17], v[16:17], v[216:217] op_sel_hi:[1,0]
	v_pk_mul_f32 v[18:19], v[18:19], v[216:217] op_sel_hi:[1,0]
	v_pk_mul_f32 v[20:21], v[20:21], v[216:217] op_sel_hi:[1,0]
	v_pk_mul_f32 v[22:23], v[22:23], v[216:217] op_sel_hi:[1,0]
	v_pk_mul_f32 v[24:25], v[24:25], v[216:217] op_sel_hi:[1,0]
	v_pk_mul_f32 v[26:27], v[26:27], v[216:217] op_sel_hi:[1,0]
	v_pk_mul_f32 v[28:29], v[28:29], v[216:217] op_sel_hi:[1,0]
	v_pk_mul_f32 v[30:31], v[30:31], v[216:217] op_sel_hi:[1,0]
	v_pk_mul_f32 v[0:1], v[0:1], v[216:217] op_sel_hi:[1,0]
	v_pk_mul_f32 v[2:3], v[2:3], v[216:217] op_sel_hi:[1,0]
	v_pk_mul_f32 v[4:5], v[4:5], v[216:217] op_sel_hi:[1,0]
	v_pk_mul_f32 v[6:7], v[6:7], v[216:217] op_sel_hi:[1,0]
	v_pk_mul_f32 v[8:9], v[8:9], v[216:217] op_sel_hi:[1,0]
	v_pk_mul_f32 v[10:11], v[10:11], v[216:217] op_sel_hi:[1,0]
	v_pk_mul_f32 v[12:13], v[12:13], v[216:217] op_sel_hi:[1,0]
	v_pk_mul_f32 v[14:15], v[14:15], v[216:217] op_sel_hi:[1,0]
